# A loop exp groups start two MFMA gaps earlier (row sum chained in a spare VGPR), C loop K/forget-bias LDS reads issued right after the barrier, xcd barrier at phase 0
# baseline (speedup 1.0000x reference)
; DI float max3f(float a, float b, float c) { float r; asm("v_max3_f32 %0, %1, %2, %3" : "=v"(r) : "v"(a), "v"(b), "v"(c)); return r; }
; DI float swapmax(float m) { auto rr = __builtin_amdgcn_permlane32_swap(__float_as_uint(m), __float_as_uint(m), false, false); return fmaxf(__uint_as_float(rr[0]), __uint_as_float(rr[1])); }
; #define SBAR() __builtin_amdgcn_sched_barrier(0)
; #define MF(a_, b_, c_) __builtin_amdgcn_mfma_f32_32x32x16_bf16(a_, b_, c_, 0, 0, 0)
; #define ATT_KLD(so_, h_) do { const lds_cptr kb_ = shm3 + (so_) + ((KIND == 0) ? m * 8192 : 0) + hi * 1024 + r32 * 16 + (h_) * 4096; \
;         kf[0] = *(const LAS bf16x8*)(kb_); kf[1] = *(const LAS bf16x8*)(kb_ + 512); kf[2] = *(const LAS bf16x8*)(kb_ + 2048); kf[3] = *(const LAS bf16x8*)(kb_ + 2560); } while (0)
; #define ATT_XLD(so_) do { if (KIND == 2) { const lds_cptr xb_ = shm3 + (so_) + 32768 + r32 * 16; x0 = *(const LAS bf16x8*)(xb_); x1 = *(const LAS bf16x8*)(xb_ + 512); if (hi) { x0 = (bf16x8){0, 0, 0, 0, 0, 0, 0, 0}; x1 = x0; } } } while (0)
; template <int KIND> DI void attn_unit(const Params& P, int b, int h, int qb, char* shm, float lam, bool dry = false) {
;     ...
;     f32x16 pa0, pa1, pb0, pb1;
;     bf16x8 kf[4], x0, x1;
;     ATT_KLD(0, 0); ATT_XLD(0);
;     pa0 = MF(kf[0], qr[0], negm); pa1 = MF(kf[1], qr[0], negm); pa0 = MF(kf[2], qr[1], pa0); pa1 = MF(kf[3], qr[1], pa1);
;     SBAR(); ATT_KLD(0, 1); SBAR();
;     pa0 = MF(kf[0], qr[2], pa0); pa1 = MF(kf[1], qr[2], pa1); pa0 = MF(kf[2], qr[3], pa0); pa1 = MF(kf[3], qr[3], pa1);
;     if (KIND == 2) { pa0 = MF(x0, ones, pa0); pa1 = MF(x1, ones, pa1); }
;     ATT_FIX(pa0, pa1, ATT_TILE(0));
;     { float rm = max3f(pa0[0], pa0[1], pa1[0]), rm2 = max3f(pa0[2], pa0[3], pa1[1]); rm = max3f(rm, pa1[2], pa1[3]);
; #pragma unroll
;       for (int r = 4; r < 16; r += 4) { rm = max3f(rm, pa0[r], pa0[r + 1]); rm2 = max3f(rm2, pa0[r + 2], pa0[r + 3]); rm = max3f(rm, pa1[r], pa1[r + 1]); rm2 = max3f(rm2, pa1[r + 2], pa1[r + 3]); }
;       rm = swapmax(max3f(rm, rm2, rm2)); ATT_DECIDE(pa0, pa1, rm); }
;     for (int i = 0; i < nt_eff; ++i) {
;         ATT_STEP_BAR(i);
;         const int sn = (sc == 3 * SLOT) ? 0 : sc + SLOT;
;         const lds_cptr vp = shm3 + sc + 16384 + vlane;
;         bf16x8 vq[4]; bf16x8 pw[4]; u32x4 w0, w1; float sacc = 0.f;
;     ...
;         ATT_KLD(sn, 0); ATT_XLD(sn);
.LBB0_348:
	s_add_i32 s18, s34, 0x8400
	s_cmp_lg_u32 s34, 0x18c00
	s_cselect_b32 s29, s18, 0
	s_add_i32 s18, s29, 0
	v_add_u32_e32 v84, s18, v168
	v_add_u32_e32 v186, v84, v167
	ds_read_b128 v[100:103], v186
	ds_read_b128 v[174:177], v186 offset:512
	ds_read_b128 v[178:181], v186 offset:2048
	ds_read_b128 v[182:185], v186 offset:2560
	ds_read_b128 v[190:193], v84 offset:32768
	ds_read_b128 v[196:199], v84 offset:33280
	s_cmp_gt_u32 s35, s33
	s_cbranch_scc1 .LBB0_351
	s_lshl_b64 s[38:39], s[20:21], 13
	v_lshl_add_u64 v[84:85], v[156:157], 0, s[38:39]
	s_add_i32 s26, s41, s30
	s_mov_b32 s27, m0
	s_mov_b32 m0, s26
	s_nop 0
	global_load_lds_dwordx4 v[84:85], off
	s_mov_b32 m0, s27
	s_lshl_b64 s[38:39], s[20:21], 12
	v_lshl_add_u64 v[84:85], v[158:159], 0, s[38:39]
	s_add_i32 s26, s23, s30
	s_mov_b32 s27, m0
	s_mov_b32 m0, s26
	s_nop 0
	global_load_lds_dwordx4 v[84:85], off
	s_mov_b32 m0, s27
	s_and_b64 vcc, exec, s[42:43]
	s_cbranch_vccnz .LBB0_351
	s_lshl_b64 s[38:39], s[20:21], 10
	s_cmp_lg_u32 0, -1
	s_cselect_b32 s26, 0, 0
	s_add_i32 s26, s26, s30
	v_lshl_add_u64 v[84:85], v[160:161], 0, s[38:39]
	s_add_i32 s26, s26, 0x8000
	s_mov_b32 s27, m0
	s_mov_b32 m0, s26
	s_nop 0
	global_load_lds_dwordx4 v[84:85], off
	s_mov_b32 m0, s27

; #define SBAR() __builtin_amdgcn_sched_barrier(0)
; template <int KIND> DI void attn_unit(const Params& P, int b, int h, int qb, char* shm, float lam, bool dry = false) {
;     ...
;         const int sn = (sc == 3 * SLOT) ? 0 : sc + SLOT;
;         const lds_cptr vp = shm3 + sc + 16384 + vlane;
;         bf16x8 vq[4]; bf16x8 pw[4]; u32x4 w0, w1; float sacc = 0.f;
;     ...
;         ATT_KLD(sn, 0); ATT_XLD(sn);
;         SBAR();
;     ...
;         G1(pb0 = MF(kf[0], qr[0], negm), 0, w0, 0);  G1(pb1 = MF(kf[1], qr[0], negm), 2, w0, 1);
;         G1(pb0 = MF(kf[2], qr[1], pb0), 4, w0, 2);   G1(pb1 = MF(kf[3], qr[1], pb1), 6, w0, 3);
;         ATT_KLD(sn, 1);
;         SBAR();
;         G1(pb0 = MF(kf[0], qr[2], pb0), 8, w1, 0);   G1(pb1 = MF(kf[1], qr[2], pb1), 10, w1, 1);
;         LDV(0); SBAR();
;         G1(pb0 = MF(kf[2], qr[3], pb0), 12, w1, 2);
;         LDV(1); SBAR();
;         G1(pb1 = MF(kf[3], qr[3], pb1), 14, w1, 3);
;         LDV(2); SBAR();
;     ...
;         if (KIND == 2) { pb0 = MF(x0, ones, pb0); pb1 = MF(x1, ones, pb1); }
;         pw[0] = __builtin_bit_cast(bf16x8, w0); pw[1] = __builtin_bit_cast(bf16x8, w1);
;     ...
;         if (NDB == 4) {
;             LDV(3); PVM(0); E4(0, w0, 0); PIN(pa1); PIN(sacc); PIN(w0); SBAR();
;             LDV(4); PVM(1); E4(2, w0, 1); PIN(pa1); PIN(sacc); PIN(w0); SBAR();
;             LDV(5); PVM(2); E4(4, w0, 2); PIN(pa1); PIN(sacc); PIN(w0); SBAR();
;             LDV(6); PVM(3); E4(6, w0, 3); PIN(pa1); PIN(sacc); PIN(w0); SBAR();
;             LDV(7); PVM(4); E4(8, w1, 0); PIN(pa1); PIN(sacc); PIN(w1); SBAR();
;             LDV(8); PVM(5); E4(10, w1, 1); PIN(pa1); PIN(sacc); PIN(w1); SBAR();
;             LDV(9); PVM(6); E4(12, w1, 2); PIN(pa1); PIN(sacc); PIN(w1); SBAR();
;             LDV(10); PVM(7); E4(14, w1, 3); PIN(pa1); PIN(sacc); PIN(w1); SBAR();
;         } else {
;             LDV(3); PVM(0); E4(0, w0, 0); E4(2, w0, 1); PIN(pa1); PIN(sacc); PIN(w0); SBAR();
;             LDV(4); PVM(1); E4(4, w0, 2); E4(6, w0, 3); PIN(pa1); PIN(sacc); PIN(w0); SBAR();
;             LDV(5); PVM(2); E4(8, w1, 0); E4(10, w1, 1); PIN(pa1); PIN(sacc); PIN(w1); SBAR();
;             LDV(6); PVM(3); E4(12, w1, 2); E4(14, w1, 3); PIN(pa1); PIN(sacc); PIN(w1); SBAR();
;         }
;     ...
;         pw[2] = __builtin_bit_cast(bf16x8, w0); pw[3] = __builtin_bit_cast(bf16x8, w1);
;         lsum += sacc;
;         ATT_FIX(pb0, pb1, ATT_TILE(i + 1));
.LBB0_355:
	v_exp_f32_e32 v116, v116
	v_exp_f32_e32 v117, v117
	s_nop 0
	v_cvt_pk_bf16_f32 v152, v116, v117
	v_add_f32_e32 v84, 0, v116
	v_add_f32_e32 v84, v117, v84
	v_exp_f32_e32 v118, v118
	v_exp_f32_e32 v119, v119
	v_add_f32_e32 v84, v84, v118
	v_add_f32_e32 v84, v119, v84
	v_cvt_pk_bf16_f32 v153, v118, v119
	v_exp_f32_e32 v120, v120
	v_exp_f32_e32 v121, v121
	v_add_f32_e32 v84, v84, v120
	v_add_f32_e32 v187, v121, v84
	v_cvt_pk_bf16_f32 v154, v120, v121
	s_waitcnt lgkmcnt(5)
	v_mfma_f32_32x32x16_bf16 v[84:99], v[100:103], v[144:147], v[20:35]
	v_exp_f32_e32 v122, v122
	v_exp_f32_e32 v123, v123
	s_waitcnt lgkmcnt(4)
	v_mfma_f32_32x32x16_bf16 v[100:115], v[174:177], v[144:147], v[20:35]
	s_add_i32 s18, s34, 0
	v_exp_f32_e32 v124, v124
	v_exp_f32_e32 v125, v125
	s_waitcnt lgkmcnt(3)
	v_mfma_f32_32x32x16_bf16 v[84:99], v[178:181], v[140:143], v[84:99]
	v_add3_u32 v68, s18, v170, v171
	v_add_f32_e32 v72, v187, v122
	v_cvt_pk_bf16_f32 v148, v124, v125
	v_add_u32_e32 v164, v68, v172
	s_waitcnt lgkmcnt(0)
	v_add_f32_e32 v187, v123, v72
	v_cvt_pk_bf16_f32 v155, v122, v123
	v_mfma_f32_32x32x16_bf16 v[100:115], v[182:185], v[140:143], v[100:115]
	ds_read_b128 v[72:75], v186 offset:4096
	ds_read_b128 v[80:83], v186 offset:4608
	ds_read_b128 v[174:177], v186 offset:6144
	ds_read_b128 v[178:181], v186 offset:6656
	s_waitcnt lgkmcnt(3)
	v_mfma_f32_32x32x16_bf16 v[84:99], v[72:75], v[136:139], v[84:99]
	v_add_f32_e32 v72, v187, v124
	v_add_f32_e32 v72, v125, v72
	s_waitcnt lgkmcnt(2)
	v_mfma_f32_32x32x16_bf16 v[100:115], v[80:83], v[136:139], v[100:115]
	v_exp_f32_e32 v126, v126
	v_exp_f32_e32 v127, v127
	v_add_f32_e32 v72, v72, v126
	v_add_f32_e32 v80, v127, v72
	v_cvt_pk_bf16_f32 v149, v126, v127
	ds_read_b64_tr_b16 v[72:73], v164 offset:16384
	ds_read_b64_tr_b16 v[74:75], v164 offset:16896
	s_waitcnt lgkmcnt(3)
	v_mfma_f32_32x32x16_bf16 v[84:99], v[174:177], v[132:135], v[84:99]
	v_exp_f32_e32 v128, v128
	v_exp_f32_e32 v129, v129
	v_add_f32_e32 v80, v80, v128
	v_add_f32_e32 v174, v129, v80
	v_cvt_pk_bf16_f32 v150, v128, v129
	ds_read_b64_tr_b16 v[80:81], v164 offset:20480
	ds_read_b64_tr_b16 v[82:83], v164 offset:20992
	s_waitcnt lgkmcnt(4)
	v_mfma_f32_32x32x16_bf16 v[100:115], v[178:181], v[132:135], v[100:115]
	v_exp_f32_e32 v130, v130
	v_exp_f32_e32 v131, v131
	v_add_f32_e32 v151, v174, v130
	v_add_f32_e32 v174, v131, v151
	v_cvt_pk_bf16_f32 v151, v130, v131
	ds_read_b64_tr_b16 v[124:125], v164 offset:17408
	ds_read_b64_tr_b16 v[126:127], v164 offset:17920
	v_mfma_f32_32x32x16_bf16 v[84:99], v[190:193], v[0:3], v[84:99]
	v_exp_f32_e32 v4, v4
	v_exp_f32_e32 v5, v5
	v_exp_f32_e32 v6, v6
	v_exp_f32_e32 v7, v7
	v_cvt_pk_bf16_f32 v190, v4, v5
	v_mfma_f32_32x32x16_bf16 v[100:115], v[196:199], v[0:3], v[100:115]
	ds_read_b64_tr_b16 v[68:69], v164 offset:21504
	ds_read_b64_tr_b16 v[70:71], v164 offset:22016
	s_waitcnt lgkmcnt(6)
	v_mfma_f32_32x32x16_bf16 v[52:67], v[72:75], v[152:155], v[52:67]
	v_add_f32_e32 v72, v4, v174
	v_add_f32_e32 v76, v5, v72
	v_add_f32_e32 v73, v6, v76
	v_add_f32_e32 v76, v7, v73
	v_cvt_pk_bf16_f32 v191, v6, v7
	v_exp_f32_e32 v8, v8
	v_exp_f32_e32 v9, v9
	s_waitcnt lgkmcnt(4)
	v_mfma_f32_32x32x16_bf16 v[36:51], v[80:83], v[152:155], v[36:51]
	v_exp_f32_e32 v10, v10
	v_exp_f32_e32 v11, v11
	v_add_f32_e32 v74, v76, v8
	ds_read_b64_tr_b16 v[116:117], v164 offset:18432
	ds_read_b64_tr_b16 v[118:119], v164 offset:18944
	v_add_f32_e32 v75, v9, v74
	v_add_f32_e32 v75, v10, v75
	v_cvt_pk_bf16_f32 v192, v8, v9
	v_add_f32_e32 v76, v11, v75
	v_cvt_pk_bf16_f32 v193, v10, v11
	v_exp_f32_e32 v12, v12
	s_waitcnt lgkmcnt(4)
	v_mfma_f32_32x32x16_bf16 v[52:67], v[124:127], v[148:151], v[52:67]
	v_exp_f32_e32 v13, v13
	v_exp_f32_e32 v14, v14
	ds_read_b64_tr_b16 v[120:121], v164 offset:22528
	ds_read_b64_tr_b16 v[122:123], v164 offset:23040
	v_exp_f32_e32 v15, v15
	v_add_f32_e32 v72, v76, v12
	v_add_f32_e32 v76, v13, v72
	v_cvt_pk_bf16_f32 v152, v12, v13
	v_add_f32_e32 v73, v14, v76
	v_add_f32_e32 v76, v15, v73
	v_cvt_pk_bf16_f32 v153, v14, v15
	s_waitcnt lgkmcnt(4)
	v_mfma_f32_32x32x16_bf16 v[36:51], v[68:71], v[148:151], v[36:51]
	v_exp_f32_e32 v16, v16
	v_exp_f32_e32 v17, v17
	v_exp_f32_e32 v18, v18
	v_exp_f32_e32 v19, v19
	ds_read_b64_tr_b16 v[124:125], v164 offset:19456
	ds_read_b64_tr_b16 v[126:127], v164 offset:19968
	v_add_f32_e32 v68, v76, v16
	v_add_f32_e32 v68, v17, v68
	v_cvt_pk_bf16_f32 v154, v16, v17
	v_cvt_pk_bf16_f32 v155, v18, v19
	v_add_f32_e32 v68, v18, v68
	v_add_f32_e32 v68, v19, v68
	s_cmp_lg_u32 s22, s35
	s_cbranch_scc1 .LBB0_357
	v_cndmask_b32_e64 v4, v84, v245, s[48:49]
	v_cndmask_b32_e64 v100, v100, v245, s[50:51]
	v_cndmask_b32_e64 v85, v245, v85, s[52:53]
	v_cndmask_b32_e64 v84, v4, v84, s[52:53]
	v_cndmask_b32_e64 v101, v101, v245, s[54:55]
	v_cndmask_b32_e64 v86, v86, v245, s[56:57]
	v_cndmask_b32_e64 v102, v102, v245, s[58:59]
	v_cndmask_b32_e64 v87, v87, v245, s[60:61]
	v_cndmask_b32_e64 v103, v103, v245, s[62:63]
	v_cndmask_b32_e64 v88, v88, v245, s[64:65]
	v_cndmask_b32_e64 v104, v104, v245, s[66:67]
	v_cndmask_b32_e64 v89, v89, v245, s[68:69]
	v_cndmask_b32_e64 v105, v105, v245, s[70:71]
	v_cndmask_b32_e64 v90, v90, v245, s[72:73]
	v_cndmask_b32_e64 v106, v106, v245, s[74:75]
	v_cndmask_b32_e64 v91, v91, v245, s[76:77]
	v_cndmask_b32_e64 v107, v107, v245, s[78:79]
	v_cndmask_b32_e64 v92, v92, v245, s[80:81]
	v_cndmask_b32_e64 v108, v108, v245, s[82:83]
	v_cndmask_b32_e64 v93, v93, v245, s[84:85]
	v_cndmask_b32_e64 v109, v109, v245, s[86:87]
	v_cndmask_b32_e64 v94, v94, v245, s[88:89]
	v_cndmask_b32_e64 v110, v110, v245, s[90:91]
	v_cndmask_b32_e64 v95, v95, v245, s[92:93]
	v_cndmask_b32_e64 v111, v111, v245, s[94:95]
	v_cndmask_b32_e64 v96, v96, v245, s[96:97]
	v_cndmask_b32_e64 v112, v112, v245, s[4:5]
	v_cndmask_b32_e64 v97, v97, v245, s[6:7]
	v_cndmask_b32_e64 v113, v113, v245, s[8:9]
	v_cndmask_b32_e64 v98, v98, v245, s[10:11]
	v_cndmask_b32_e64 v114, v114, v245, s[12:13]
	v_cndmask_b32_e64 v99, v99, v245, s[14:15]
	v_cndmask_b32_e64 v115, v115, v245, s[16:17]

; DI float max3f(float a, float b, float c) { float r; asm("v_max3_f32 %0, %1, %2, %3" : "=v"(r) : "v"(a), "v"(b), "v"(c)); return r; }
; DI float swapmax(float m) { auto rr = __builtin_amdgcn_permlane32_swap(__float_as_uint(m), __float_as_uint(m), false, false); return fmaxf(__uint_as_float(rr[0]), __uint_as_float(rr[1])); }
; #define SBAR() __builtin_amdgcn_sched_barrier(0)
; #define MF(a_, b_, c_) __builtin_amdgcn_mfma_f32_32x32x16_bf16(a_, b_, c_, 0, 0, 0)
; #define ATT_KLD(so_, h_) do { const lds_cptr kb_ = shm3 + (so_) + ((KIND == 0) ? m * 8192 : 0) + hi * 1024 + r32 * 16 + (h_) * 4096; \
;         kf[0] = *(const LAS bf16x8*)(kb_); kf[1] = *(const LAS bf16x8*)(kb_ + 512); kf[2] = *(const LAS bf16x8*)(kb_ + 2048); kf[3] = *(const LAS bf16x8*)(kb_ + 2560); } while (0)
; #define ATT_XLD(so_) do { if (KIND == 2) { const lds_cptr xb_ = shm3 + (so_) + 32768 + r32 * 16; x0 = *(const LAS bf16x8*)(xb_); x1 = *(const LAS bf16x8*)(xb_ + 512); if (hi) { x0 = (bf16x8){0, 0, 0, 0, 0, 0, 0, 0}; x1 = x0; } } } while (0)
; template <int KIND> DI void attn_unit(const Params& P, int b, int h, int qb, char* shm, float lam, bool dry = false) {
;     ...
;     f32x16 pa0, pa1, pb0, pb1;
;     bf16x8 kf[4], x0, x1;
;     ATT_KLD(0, 0); ATT_XLD(0);
;     pa0 = MF(kf[0], qr[0], negm); pa1 = MF(kf[1], qr[0], negm); pa0 = MF(kf[2], qr[1], pa0); pa1 = MF(kf[3], qr[1], pa1);
;     SBAR(); ATT_KLD(0, 1); SBAR();
;     pa0 = MF(kf[0], qr[2], pa0); pa1 = MF(kf[1], qr[2], pa1); pa0 = MF(kf[2], qr[3], pa0); pa1 = MF(kf[3], qr[3], pa1);
;     if (KIND == 2) { pa0 = MF(x0, ones, pa0); pa1 = MF(x1, ones, pa1); }
;     ATT_FIX(pa0, pa1, ATT_TILE(0));
;     { float rm = max3f(pa0[0], pa0[1], pa1[0]), rm2 = max3f(pa0[2], pa0[3], pa1[1]); rm = max3f(rm, pa1[2], pa1[3]);
; #pragma unroll
;       for (int r = 4; r < 16; r += 4) { rm = max3f(rm, pa0[r], pa0[r + 1]); rm2 = max3f(rm2, pa0[r + 2], pa0[r + 3]); rm = max3f(rm, pa1[r], pa1[r + 1]); rm2 = max3f(rm2, pa1[r + 2], pa1[r + 3]); }
;       rm = swapmax(max3f(rm, rm2, rm2)); ATT_DECIDE(pa0, pa1, rm); }
;     for (int i = 0; i < nt_eff; ++i) {
;         ATT_STEP_BAR(i);
;         const int sn = (sc == 3 * SLOT) ? 0 : sc + SLOT;
;         const lds_cptr vp = shm3 + sc + 16384 + vlane;
;         bf16x8 vq[4]; bf16x8 pw[4]; u32x4 w0, w1; float sacc = 0.f;
;     ...
;         ATT_KLD(sn, 0); ATT_XLD(sn);
.Lct2_348:
	s_add_i32 s18, s34, 0x8400
	s_cmp_lg_u32 s34, 0x18c00
	s_cselect_b32 s29, s18, 0
	s_add_i32 s18, s29, 0
	v_add_u32_e32 v116, s18, v168
	v_add_u32_e32 v186, v116, v167
	ds_read_b128 v[4:7], v186
	ds_read_b128 v[174:177], v186 offset:512
	ds_read_b128 v[178:181], v186 offset:2048
	ds_read_b128 v[182:185], v186 offset:2560
	ds_read_b128 v[190:193], v116 offset:32768
	ds_read_b128 v[196:199], v116 offset:33280
	s_cmp_gt_u32 s35, s33
	s_cbranch_scc1 .Lct2_351
	s_lshl_b64 s[38:39], s[20:21], 13
	v_lshl_add_u64 v[116:117], v[156:157], 0, s[38:39]
	s_add_i32 s26, s41, s30
	s_mov_b32 s27, m0
	s_mov_b32 m0, s26
	s_nop 0
	global_load_lds_dwordx4 v[116:117], off
	s_mov_b32 m0, s27
	s_lshl_b64 s[38:39], s[20:21], 12
	v_lshl_add_u64 v[116:117], v[158:159], 0, s[38:39]
	s_add_i32 s26, s23, s30
	s_mov_b32 s27, m0
	s_mov_b32 m0, s26
	s_nop 0
	global_load_lds_dwordx4 v[116:117], off
	s_mov_b32 m0, s27
	s_and_b64 vcc, exec, s[42:43]
	s_cbranch_vccnz .Lct2_351
	s_lshl_b64 s[38:39], s[20:21], 10
	s_cmp_lg_u32 0, -1
	s_cselect_b32 s26, 0, 0
	s_add_i32 s26, s26, s30
	v_lshl_add_u64 v[116:117], v[160:161], 0, s[38:39]
	s_add_i32 s26, s26, 0x8000
	s_mov_b32 s27, m0
	s_mov_b32 m0, s26
	s_nop 0
	global_load_lds_dwordx4 v[116:117], off
	s_mov_b32 m0, s27

; #define SBAR() __builtin_amdgcn_sched_barrier(0)
; template <int KIND> DI void attn_unit(const Params& P, int b, int h, int qb, char* shm, float lam, bool dry = false) {
;     ...
;         const int sn = (sc == 3 * SLOT) ? 0 : sc + SLOT;
;         const lds_cptr vp = shm3 + sc + 16384 + vlane;
;         bf16x8 vq[4]; bf16x8 pw[4]; u32x4 w0, w1; float sacc = 0.f;
;     ...
;         ATT_KLD(sn, 0); ATT_XLD(sn);
;         SBAR();
;     ...
;         G1(pb0 = MF(kf[0], qr[0], negm), 0, w0, 0);  G1(pb1 = MF(kf[1], qr[0], negm), 2, w0, 1);
;         G1(pb0 = MF(kf[2], qr[1], pb0), 4, w0, 2);   G1(pb1 = MF(kf[3], qr[1], pb1), 6, w0, 3);
;         ATT_KLD(sn, 1);
;         SBAR();
;         G1(pb0 = MF(kf[0], qr[2], pb0), 8, w1, 0);   G1(pb1 = MF(kf[1], qr[2], pb1), 10, w1, 1);
;         LDV(0); SBAR();
;         G1(pb0 = MF(kf[2], qr[3], pb0), 12, w1, 2);
;         LDV(1); SBAR();
;         G1(pb1 = MF(kf[3], qr[3], pb1), 14, w1, 3);
;         LDV(2); SBAR();
;     ...
;         if (KIND == 2) { pb0 = MF(x0, ones, pb0); pb1 = MF(x1, ones, pb1); }
;         pw[0] = __builtin_bit_cast(bf16x8, w0); pw[1] = __builtin_bit_cast(bf16x8, w1);
;     ...
;         if (NDB == 4) {
;             LDV(3); PVM(0); E4(0, w0, 0); PIN(pa1); PIN(sacc); PIN(w0); SBAR();
;             LDV(4); PVM(1); E4(2, w0, 1); PIN(pa1); PIN(sacc); PIN(w0); SBAR();
;             LDV(5); PVM(2); E4(4, w0, 2); PIN(pa1); PIN(sacc); PIN(w0); SBAR();
;             LDV(6); PVM(3); E4(6, w0, 3); PIN(pa1); PIN(sacc); PIN(w0); SBAR();
;             LDV(7); PVM(4); E4(8, w1, 0); PIN(pa1); PIN(sacc); PIN(w1); SBAR();
;             LDV(8); PVM(5); E4(10, w1, 1); PIN(pa1); PIN(sacc); PIN(w1); SBAR();
;             LDV(9); PVM(6); E4(12, w1, 2); PIN(pa1); PIN(sacc); PIN(w1); SBAR();
;             LDV(10); PVM(7); E4(14, w1, 3); PIN(pa1); PIN(sacc); PIN(w1); SBAR();
;         } else {
;             LDV(3); PVM(0); E4(0, w0, 0); E4(2, w0, 1); PIN(pa1); PIN(sacc); PIN(w0); SBAR();
;             LDV(4); PVM(1); E4(4, w0, 2); E4(6, w0, 3); PIN(pa1); PIN(sacc); PIN(w0); SBAR();
;             LDV(5); PVM(2); E4(8, w1, 0); E4(10, w1, 1); PIN(pa1); PIN(sacc); PIN(w1); SBAR();
;             LDV(6); PVM(3); E4(12, w1, 2); E4(14, w1, 3); PIN(pa1); PIN(sacc); PIN(w1); SBAR();
;         }
;     ...
;         pw[2] = __builtin_bit_cast(bf16x8, w0); pw[3] = __builtin_bit_cast(bf16x8, w1);
;         lsum += sacc;
;         ATT_FIX(pb0, pb1, ATT_TILE(i + 1));
.Lct2_355:
	v_exp_f32_e32 v84, v84
	v_exp_f32_e32 v85, v85
	s_nop 0
	v_cvt_pk_bf16_f32 v152, v84, v85
	v_add_f32_e32 v116, 0, v84
	v_add_f32_e32 v116, v85, v116
	v_exp_f32_e32 v86, v86
	v_exp_f32_e32 v87, v87
	v_add_f32_e32 v116, v116, v86
	v_add_f32_e32 v116, v87, v116
	v_cvt_pk_bf16_f32 v153, v86, v87
	v_exp_f32_e32 v88, v88
	v_exp_f32_e32 v89, v89
	v_add_f32_e32 v116, v116, v88
	v_add_f32_e32 v187, v89, v116
	v_cvt_pk_bf16_f32 v154, v88, v89
	s_waitcnt lgkmcnt(5)
	v_mfma_f32_32x32x16_bf16 v[116:131], v[4:7], v[144:147], v[20:35]
	v_exp_f32_e32 v90, v90
	v_exp_f32_e32 v91, v91
	s_waitcnt lgkmcnt(4)
	v_mfma_f32_32x32x16_bf16 v[4:19], v[174:177], v[144:147], v[20:35]
	s_add_i32 s18, s34, 0
	v_exp_f32_e32 v92, v92
	v_exp_f32_e32 v93, v93
	s_waitcnt lgkmcnt(3)
	v_mfma_f32_32x32x16_bf16 v[116:131], v[178:181], v[140:143], v[116:131]
	v_add3_u32 v68, s18, v170, v171
	v_add_f32_e32 v72, v187, v90
	v_cvt_pk_bf16_f32 v148, v92, v93
	v_add_u32_e32 v164, v68, v172
	s_waitcnt lgkmcnt(0)
	v_add_f32_e32 v187, v91, v72
	v_cvt_pk_bf16_f32 v155, v90, v91
	v_mfma_f32_32x32x16_bf16 v[4:19], v[182:185], v[140:143], v[4:19]
	ds_read_b128 v[72:75], v186 offset:4096
	ds_read_b128 v[80:83], v186 offset:4608
	ds_read_b128 v[174:177], v186 offset:6144
	ds_read_b128 v[178:181], v186 offset:6656
	s_waitcnt lgkmcnt(3)
	v_mfma_f32_32x32x16_bf16 v[116:131], v[72:75], v[136:139], v[116:131]
	v_add_f32_e32 v72, v187, v92
	v_add_f32_e32 v72, v93, v72
	s_waitcnt lgkmcnt(2)
	v_mfma_f32_32x32x16_bf16 v[4:19], v[80:83], v[136:139], v[4:19]
	v_exp_f32_e32 v94, v94
	v_exp_f32_e32 v95, v95
	v_add_f32_e32 v72, v72, v94
	v_add_f32_e32 v80, v95, v72
	v_cvt_pk_bf16_f32 v149, v94, v95
	ds_read_b64_tr_b16 v[72:73], v164 offset:16384
	ds_read_b64_tr_b16 v[74:75], v164 offset:16896
	s_waitcnt lgkmcnt(3)
	v_mfma_f32_32x32x16_bf16 v[116:131], v[174:177], v[132:135], v[116:131]
	v_exp_f32_e32 v96, v96
	v_exp_f32_e32 v97, v97
	v_add_f32_e32 v80, v80, v96
	v_add_f32_e32 v174, v97, v80
	v_cvt_pk_bf16_f32 v150, v96, v97
	ds_read_b64_tr_b16 v[80:81], v164 offset:20480
	ds_read_b64_tr_b16 v[82:83], v164 offset:20992
	s_waitcnt lgkmcnt(4)
	v_mfma_f32_32x32x16_bf16 v[4:19], v[178:181], v[132:135], v[4:19]
	v_exp_f32_e32 v98, v98
	v_exp_f32_e32 v99, v99
	v_add_f32_e32 v151, v174, v98
	v_add_f32_e32 v174, v99, v151
	v_cvt_pk_bf16_f32 v151, v98, v99
	ds_read_b64_tr_b16 v[92:93], v164 offset:17408
	ds_read_b64_tr_b16 v[94:95], v164 offset:17920
	v_mfma_f32_32x32x16_bf16 v[116:131], v[190:193], v[0:3], v[116:131]
	v_exp_f32_e32 v100, v100
	v_exp_f32_e32 v101, v101
	v_exp_f32_e32 v102, v102
	v_exp_f32_e32 v103, v103
	v_cvt_pk_bf16_f32 v190, v100, v101
	v_mfma_f32_32x32x16_bf16 v[4:19], v[196:199], v[0:3], v[4:19]
	ds_read_b64_tr_b16 v[68:69], v164 offset:21504
	ds_read_b64_tr_b16 v[70:71], v164 offset:22016
	s_waitcnt lgkmcnt(6)
	v_mfma_f32_32x32x16_bf16 v[52:67], v[72:75], v[152:155], v[52:67]
	v_add_f32_e32 v72, v100, v174
	v_add_f32_e32 v76, v101, v72
	v_add_f32_e32 v73, v102, v76
	v_add_f32_e32 v76, v103, v73
	v_cvt_pk_bf16_f32 v191, v102, v103
	v_exp_f32_e32 v104, v104
	v_exp_f32_e32 v105, v105
	s_waitcnt lgkmcnt(4)
	v_mfma_f32_32x32x16_bf16 v[36:51], v[80:83], v[152:155], v[36:51]
	v_exp_f32_e32 v106, v106
	v_exp_f32_e32 v107, v107
	v_add_f32_e32 v74, v76, v104
	ds_read_b64_tr_b16 v[84:85], v164 offset:18432
	ds_read_b64_tr_b16 v[86:87], v164 offset:18944
	v_add_f32_e32 v75, v105, v74
	v_add_f32_e32 v75, v106, v75
	v_cvt_pk_bf16_f32 v192, v104, v105
	v_add_f32_e32 v76, v107, v75
	v_cvt_pk_bf16_f32 v193, v106, v107
	v_exp_f32_e32 v108, v108
	s_waitcnt lgkmcnt(4)
	v_mfma_f32_32x32x16_bf16 v[52:67], v[92:95], v[148:151], v[52:67]
	v_exp_f32_e32 v109, v109
	v_exp_f32_e32 v110, v110
	ds_read_b64_tr_b16 v[88:89], v164 offset:22528
	ds_read_b64_tr_b16 v[90:91], v164 offset:23040
	v_exp_f32_e32 v111, v111
	v_add_f32_e32 v72, v76, v108
	v_add_f32_e32 v76, v109, v72
	v_cvt_pk_bf16_f32 v152, v108, v109
	v_add_f32_e32 v73, v110, v76
	v_add_f32_e32 v76, v111, v73
	v_cvt_pk_bf16_f32 v153, v110, v111
	s_waitcnt lgkmcnt(4)
	v_mfma_f32_32x32x16_bf16 v[36:51], v[68:71], v[148:151], v[36:51]
	v_exp_f32_e32 v112, v112
	v_exp_f32_e32 v113, v113
	v_exp_f32_e32 v114, v114
	v_exp_f32_e32 v115, v115
	ds_read_b64_tr_b16 v[92:93], v164 offset:19456
	ds_read_b64_tr_b16 v[94:95], v164 offset:19968
	v_add_f32_e32 v68, v76, v112
	v_add_f32_e32 v68, v113, v68
	v_cvt_pk_bf16_f32 v154, v112, v113
	v_cvt_pk_bf16_f32 v155, v114, v115
	v_add_f32_e32 v68, v114, v68
	v_add_f32_e32 v68, v115, v68
	s_cmp_lg_u32 s22, s35
	s_cbranch_scc1 .Lct2_357
	v_cndmask_b32_e64 v100, v116, v245, s[48:49]
	v_cndmask_b32_e64 v4, v4, v245, s[50:51]
	v_cndmask_b32_e64 v117, v245, v117, s[52:53]
	v_cndmask_b32_e64 v116, v100, v116, s[52:53]
	v_cndmask_b32_e64 v5, v5, v245, s[54:55]
	v_cndmask_b32_e64 v118, v118, v245, s[56:57]
	v_cndmask_b32_e64 v6, v6, v245, s[58:59]
	v_cndmask_b32_e64 v119, v119, v245, s[60:61]
	v_cndmask_b32_e64 v7, v7, v245, s[62:63]
	v_cndmask_b32_e64 v120, v120, v245, s[64:65]
	v_cndmask_b32_e64 v8, v8, v245, s[66:67]
	v_cndmask_b32_e64 v121, v121, v245, s[68:69]
	v_cndmask_b32_e64 v9, v9, v245, s[70:71]
	v_cndmask_b32_e64 v122, v122, v245, s[72:73]
	v_cndmask_b32_e64 v10, v10, v245, s[74:75]
	v_cndmask_b32_e64 v123, v123, v245, s[76:77]
	v_cndmask_b32_e64 v11, v11, v245, s[78:79]
	v_cndmask_b32_e64 v124, v124, v245, s[80:81]
	v_cndmask_b32_e64 v12, v12, v245, s[82:83]
	v_cndmask_b32_e64 v125, v125, v245, s[84:85]
	v_cndmask_b32_e64 v13, v13, v245, s[86:87]
	v_cndmask_b32_e64 v126, v126, v245, s[88:89]
	v_cndmask_b32_e64 v14, v14, v245, s[90:91]
	v_cndmask_b32_e64 v127, v127, v245, s[92:93]
	v_cndmask_b32_e64 v15, v15, v245, s[94:95]
	v_cndmask_b32_e64 v128, v128, v245, s[96:97]
	v_cndmask_b32_e64 v16, v16, v245, s[4:5]
	v_cndmask_b32_e64 v129, v129, v245, s[6:7]
	v_cndmask_b32_e64 v17, v17, v245, s[8:9]
	v_cndmask_b32_e64 v130, v130, v245, s[10:11]
	v_cndmask_b32_e64 v18, v18, v245, s[12:13]
	v_cndmask_b32_e64 v131, v131, v245, s[14:15]
	v_cndmask_b32_e64 v19, v19, v245, s[16:17]

; #define SBAR() __builtin_amdgcn_sched_barrier(0)
; #define MF(a_, b_, c_) __builtin_amdgcn_mfma_f32_32x32x16_bf16(a_, b_, c_, 0, 0, 0)
; #define ATT_KLD(so_, h_) do { const lds_cptr kb_ = shm3 + (so_) + ((KIND == 0) ? m * 8192 : 0) + hi * 1024 + r32 * 16 + (h_) * 4096; \
;         kf[0] = *(const LAS bf16x8*)(kb_); kf[1] = *(const LAS bf16x8*)(kb_ + 512); kf[2] = *(const LAS bf16x8*)(kb_ + 2048); kf[3] = *(const LAS bf16x8*)(kb_ + 2560); } while (0)
; #define ATT_XLD(so_) do { if (KIND == 2) { const lds_cptr xb_ = shm3 + (so_) + 32768 + r32 * 16; x0 = *(const LAS bf16x8*)(xb_); x1 = *(const LAS bf16x8*)(xb_ + 512); if (hi) { x0 = (bf16x8){0, 0, 0, 0, 0, 0, 0, 0}; x1 = x0; } } } while (0)
; #define LDV(j_) do { if ((j_) < 4 * NDB) { const lds_cptr a_ = vp + ((j_) % NDB) * 4096 + ((j_) / NDB) * 1024; const s16x4 lo_ = vtr(a_), hi_ = vtr(a_ + 512); \
;             vq[(j_) & 3] = (bf16x8){lo_[0], lo_[1], lo_[2], lo_[3], hi_[0], hi_[1], hi_[2], hi_[3]}; } } while (0)
; #define G1(MFMA_, a_, W_, j_) do { MFMA_; pa0[a_] = EX(pa0[a_]); pa0[a_ + 1] = EX(pa0[a_ + 1]); sacc += pa0[a_]; sacc += pa0[a_ + 1]; W_[j_] = cvtpk(pa0[a_], pa0[a_ + 1]); PIN(pa0); PIN(sacc); PIN(W_); SBAR(); } while (0)
; template <int KIND> DI void attn_unit(const Params& P, int b, int h, int qb, char* shm, float lam, bool dry = false) {
;     ...
;         const int sn = (sc == 3 * SLOT) ? 0 : sc + SLOT;
;         const lds_cptr vp = shm3 + sc + 16384 + vlane;
;         bf16x8 vq[4]; bf16x8 pw[4]; u32x4 w0, w1; float sacc = 0.f;
;     ...
;         ATT_KLD(sn, 0); ATT_XLD(sn);
;         SBAR();
;     ...
;         G1(pb0 = MF(kf[0], qr[0], negm), 0, w0, 0);  G1(pb1 = MF(kf[1], qr[0], negm), 2, w0, 1);
;         G1(pb0 = MF(kf[2], qr[1], pb0), 4, w0, 2);   G1(pb1 = MF(kf[3], qr[1], pb1), 6, w0, 3);
;         ATT_KLD(sn, 1);
;         SBAR();
;         G1(pb0 = MF(kf[0], qr[2], pb0), 8, w1, 0);   G1(pb1 = MF(kf[1], qr[2], pb1), 10, w1, 1);
;         LDV(0); SBAR();
;         G1(pb0 = MF(kf[2], qr[3], pb0), 12, w1, 2);
;         LDV(1); SBAR();
;         G1(pb1 = MF(kf[3], qr[3], pb1), 14, w1, 3);
;         LDV(2); SBAR();
.LBB0_403:
	s_add_i32 s0, s5, 0x8400
	s_cmp_lg_u32 s5, 0x18c00
	s_cselect_b32 s0, s0, 0
	v_add_u32_e32 v201, s0, v193
	ds_read_b128 v[132:135], v201
	ds_read_b128 v[172:175], v201 offset:512
	ds_read_b128 v[176:179], v201 offset:2048
	ds_read_b128 v[180:183], v201 offset:2560
	v_add_u32_e32 v190, s5, v196
	v_exp_f32_e32 v100, v100
	v_exp_f32_e32 v101, v101
	v_add_f32_e32 v200, 0, v100
	v_add_f32_e32 v200, v101, v200
	v_cvt_pk_bf16_f32 v164, v100, v101
	v_exp_f32_e32 v102, v102
	v_exp_f32_e32 v103, v103
	v_add_f32_e32 v200, v200, v102
	v_add_f32_e32 v200, v103, v200
	v_cvt_pk_bf16_f32 v165, v102, v103
	s_waitcnt lgkmcnt(3)
	v_mfma_f32_32x32x16_bf16 v[116:131], v[132:135], v[160:163], v[4:19]
	v_exp_f32_e32 v104, v104
	v_exp_f32_e32 v105, v105
	v_add_f32_e32 v200, v200, v104
	v_add_f32_e32 v200, v105, v200
	v_cvt_pk_bf16_f32 v166, v104, v105
	s_waitcnt lgkmcnt(2)
	v_mfma_f32_32x32x16_bf16 v[132:147], v[172:175], v[160:163], v[4:19]
	v_exp_f32_e32 v106, v106
	v_exp_f32_e32 v107, v107
	v_add_f32_e32 v200, v200, v106
	v_add_f32_e32 v200, v107, v200
	v_cvt_pk_bf16_f32 v167, v106, v107
	s_cmp_eq_u32 s1, 0
	s_cbranch_scc1 .Lat1_nd0
	s_add_i32 m0, s11, s14
	s_nop 0
	global_load_lds_dwordx4 v[184:185], off
.Lat1_nd0:
	s_waitcnt lgkmcnt(1)
	v_mfma_f32_32x32x16_bf16 v[116:131], v[176:179], v[156:159], v[116:131]
	v_exp_f32_e32 v108, v108
	v_exp_f32_e32 v109, v109
	v_add_f32_e32 v200, v200, v108
	v_add_f32_e32 v200, v109, v200
	v_cvt_pk_bf16_f32 v168, v108, v109
	s_waitcnt lgkmcnt(0)
	v_mfma_f32_32x32x16_bf16 v[132:147], v[180:183], v[156:159], v[132:147]
	ds_read_b128 v[172:175], v201 offset:4096
	ds_read_b128 v[176:179], v201 offset:4608
	ds_read_b128 v[180:183], v201 offset:6144
	ds_read_b128 v[214:217], v201 offset:6656
	v_exp_f32_e32 v110, v110
	v_exp_f32_e32 v111, v111
	v_add_f32_e32 v200, v200, v110
	v_add_f32_e32 v200, v111, v200
	v_cvt_pk_bf16_f32 v169, v110, v111
	s_waitcnt lgkmcnt(3)
	v_mfma_f32_32x32x16_bf16 v[116:131], v[172:175], v[152:155], v[116:131]
	v_exp_f32_e32 v112, v112
	v_exp_f32_e32 v113, v113
	v_add_f32_e32 v200, v200, v112
	v_add_f32_e32 v200, v113, v200
	v_cvt_pk_bf16_f32 v170, v112, v113
	s_waitcnt lgkmcnt(2)
	v_mfma_f32_32x32x16_bf16 v[132:147], v[176:179], v[152:155], v[132:147]
	ds_read_b64_tr_b16 v[172:173], v190 offset:16384
	ds_read_b64_tr_b16 v[174:175], v190 offset:16896
	v_exp_f32_e32 v114, v114
	v_exp_f32_e32 v115, v115
	v_add_f32_e32 v200, v200, v114
	v_add_f32_e32 v200, v115, v200
	v_cvt_pk_bf16_f32 v171, v114, v115
	s_waitcnt lgkmcnt(3)
	v_mfma_f32_32x32x16_bf16 v[116:131], v[180:183], v[148:151], v[116:131]
	ds_read_b64_tr_b16 v[176:177], v190 offset:20480
	ds_read_b64_tr_b16 v[178:179], v190 offset:20992
	s_waitcnt lgkmcnt(4)
	v_mfma_f32_32x32x16_bf16 v[132:147], v[214:217], v[148:151], v[132:147]
	ds_read_b64_tr_b16 v[100:101], v190 offset:24576
	ds_read_b64_tr_b16 v[102:103], v190 offset:25088
	s_waitcnt lgkmcnt(4)
	v_mfma_f32_32x32x16_bf16 v[68:83], v[172:175], v[164:167], v[68:83]
	v_exp_f32_e32 v84, v84
	v_exp_f32_e32 v85, v85
	ds_read_b64_tr_b16 v[104:105], v190 offset:28672
	ds_read_b64_tr_b16 v[106:107], v190 offset:29184
	v_add_f32_e32 v108, v84, v200
	v_add_f32_e32 v180, v85, v108
	v_cvt_pk_bf16_f32 v108, v84, v85
	s_waitcnt lgkmcnt(4)
	v_mfma_f32_32x32x16_bf16 v[52:67], v[176:179], v[164:167], v[52:67]
	s_cmp_eq_u32 s1, 0
	s_cbranch_scc1 .Lat1_nd1
	s_add_i32 m0, s15, s14
	v_lshl_add_u64 v[214:215], v[184:185], 0, s[94:95]
	global_load_lds_dwordx4 v[214:215], off

; #define SBAR() __builtin_amdgcn_sched_barrier(0)
; #define MF(a_, b_, c_) __builtin_amdgcn_mfma_f32_32x32x16_bf16(a_, b_, c_, 0, 0, 0)
; #define ATT_KLD(so_, h_) do { const lds_cptr kb_ = shm3 + (so_) + ((KIND == 0) ? m * 8192 : 0) + hi * 1024 + r32 * 16 + (h_) * 4096; \
;         kf[0] = *(const LAS bf16x8*)(kb_); kf[1] = *(const LAS bf16x8*)(kb_ + 512); kf[2] = *(const LAS bf16x8*)(kb_ + 2048); kf[3] = *(const LAS bf16x8*)(kb_ + 2560); } while (0)
; #define ATT_XLD(so_) do { if (KIND == 2) { const lds_cptr xb_ = shm3 + (so_) + 32768 + r32 * 16; x0 = *(const LAS bf16x8*)(xb_); x1 = *(const LAS bf16x8*)(xb_ + 512); if (hi) { x0 = (bf16x8){0, 0, 0, 0, 0, 0, 0, 0}; x1 = x0; } } } while (0)
; #define LDV(j_) do { if ((j_) < 4 * NDB) { const lds_cptr a_ = vp + ((j_) % NDB) * 4096 + ((j_) / NDB) * 1024; const s16x4 lo_ = vtr(a_), hi_ = vtr(a_ + 512); \
;             vq[(j_) & 3] = (bf16x8){lo_[0], lo_[1], lo_[2], lo_[3], hi_[0], hi_[1], hi_[2], hi_[3]}; } } while (0)
; #define G1(MFMA_, a_, W_, j_) do { MFMA_; pa0[a_] = EX(pa0[a_]); pa0[a_ + 1] = EX(pa0[a_ + 1]); sacc += pa0[a_]; sacc += pa0[a_ + 1]; W_[j_] = cvtpk(pa0[a_], pa0[a_ + 1]); PIN(pa0); PIN(sacc); PIN(W_); SBAR(); } while (0)
; template <int KIND> DI void attn_unit(const Params& P, int b, int h, int qb, char* shm, float lam, bool dry = false) {
;     ...
;         const int sn = (sc == 3 * SLOT) ? 0 : sc + SLOT;
;         const lds_cptr vp = shm3 + sc + 16384 + vlane;
;         bf16x8 vq[4]; bf16x8 pw[4]; u32x4 w0, w1; float sacc = 0.f;
;     ...
;         ATT_KLD(sn, 0); ATT_XLD(sn);
;         SBAR();
;     ...
;         G1(pb0 = MF(kf[0], qr[0], negm), 0, w0, 0);  G1(pb1 = MF(kf[1], qr[0], negm), 2, w0, 1);
;         G1(pb0 = MF(kf[2], qr[1], pb0), 4, w0, 2);   G1(pb1 = MF(kf[3], qr[1], pb1), 6, w0, 3);
;         ATT_KLD(sn, 1);
;         SBAR();
;         G1(pb0 = MF(kf[0], qr[2], pb0), 8, w1, 0);   G1(pb1 = MF(kf[1], qr[2], pb1), 10, w1, 1);
;         LDV(0); SBAR();
;         G1(pb0 = MF(kf[2], qr[3], pb0), 12, w1, 2);
;         LDV(1); SBAR();
;         G1(pb1 = MF(kf[3], qr[3], pb1), 14, w1, 3);
;         LDV(2); SBAR();
.Lat2_403:
	s_add_i32 s0, s5, 0x8400
	s_cmp_lg_u32 s5, 0x18c00
	s_cselect_b32 s0, s0, 0
	v_add_u32_e32 v201, s0, v193
	ds_read_b128 v[84:87], v201
	ds_read_b128 v[172:175], v201 offset:512
	ds_read_b128 v[176:179], v201 offset:2048
	ds_read_b128 v[180:183], v201 offset:2560
	v_add_u32_e32 v190, s5, v196
	v_exp_f32_e32 v116, v116
	v_exp_f32_e32 v117, v117
	v_add_f32_e32 v200, 0, v116
	v_add_f32_e32 v200, v117, v200
	v_cvt_pk_bf16_f32 v164, v116, v117
	v_exp_f32_e32 v118, v118
	v_exp_f32_e32 v119, v119
	v_add_f32_e32 v200, v200, v118
	v_add_f32_e32 v200, v119, v200
	v_cvt_pk_bf16_f32 v165, v118, v119
	s_waitcnt lgkmcnt(3)
	v_mfma_f32_32x32x16_bf16 v[100:115], v[84:87], v[160:163], v[4:19]
	v_exp_f32_e32 v120, v120
	v_exp_f32_e32 v121, v121
	v_add_f32_e32 v200, v200, v120
	v_add_f32_e32 v200, v121, v200
	v_cvt_pk_bf16_f32 v166, v120, v121
	s_waitcnt lgkmcnt(2)
	v_mfma_f32_32x32x16_bf16 v[84:99], v[172:175], v[160:163], v[4:19]
	v_exp_f32_e32 v122, v122
	v_exp_f32_e32 v123, v123
	v_add_f32_e32 v200, v200, v122
	v_add_f32_e32 v200, v123, v200
	v_cvt_pk_bf16_f32 v167, v122, v123
	s_cmp_eq_u32 s1, 0
	s_cbranch_scc1 .Lat2_nd0
	s_add_i32 m0, s11, s14
	s_nop 0
	global_load_lds_dwordx4 v[184:185], off
.Lat2_nd0:
	s_waitcnt lgkmcnt(1)
	v_mfma_f32_32x32x16_bf16 v[100:115], v[176:179], v[156:159], v[100:115]
	v_exp_f32_e32 v124, v124
	v_exp_f32_e32 v125, v125
	v_add_f32_e32 v200, v200, v124
	v_add_f32_e32 v200, v125, v200
	v_cvt_pk_bf16_f32 v168, v124, v125
	s_waitcnt lgkmcnt(0)
	v_mfma_f32_32x32x16_bf16 v[84:99], v[180:183], v[156:159], v[84:99]
	ds_read_b128 v[172:175], v201 offset:4096
	ds_read_b128 v[176:179], v201 offset:4608
	ds_read_b128 v[180:183], v201 offset:6144
	ds_read_b128 v[214:217], v201 offset:6656
	v_exp_f32_e32 v126, v126
	v_exp_f32_e32 v127, v127
	v_add_f32_e32 v200, v200, v126
	v_add_f32_e32 v200, v127, v200
	v_cvt_pk_bf16_f32 v169, v126, v127
	s_waitcnt lgkmcnt(3)
	v_mfma_f32_32x32x16_bf16 v[100:115], v[172:175], v[152:155], v[100:115]
	v_exp_f32_e32 v128, v128
	v_exp_f32_e32 v129, v129
	v_add_f32_e32 v200, v200, v128
	v_add_f32_e32 v200, v129, v200
	v_cvt_pk_bf16_f32 v170, v128, v129
	s_waitcnt lgkmcnt(2)
	v_mfma_f32_32x32x16_bf16 v[84:99], v[176:179], v[152:155], v[84:99]
	ds_read_b64_tr_b16 v[172:173], v190 offset:16384
	ds_read_b64_tr_b16 v[174:175], v190 offset:16896
	v_exp_f32_e32 v130, v130
	v_exp_f32_e32 v131, v131
	v_add_f32_e32 v200, v200, v130
	v_add_f32_e32 v200, v131, v200
	v_cvt_pk_bf16_f32 v171, v130, v131
	s_waitcnt lgkmcnt(3)
	v_mfma_f32_32x32x16_bf16 v[100:115], v[180:183], v[148:151], v[100:115]
	ds_read_b64_tr_b16 v[176:177], v190 offset:20480
	ds_read_b64_tr_b16 v[178:179], v190 offset:20992
	s_waitcnt lgkmcnt(4)
	v_mfma_f32_32x32x16_bf16 v[84:99], v[214:217], v[148:151], v[84:99]
	ds_read_b64_tr_b16 v[116:117], v190 offset:24576
	ds_read_b64_tr_b16 v[118:119], v190 offset:25088
	s_waitcnt lgkmcnt(4)
	v_mfma_f32_32x32x16_bf16 v[68:83], v[172:175], v[164:167], v[68:83]
	v_exp_f32_e32 v132, v132
	v_exp_f32_e32 v133, v133
	ds_read_b64_tr_b16 v[120:121], v190 offset:28672
	ds_read_b64_tr_b16 v[122:123], v190 offset:29184
	v_add_f32_e32 v124, v132, v200
	v_add_f32_e32 v180, v133, v124
	v_cvt_pk_bf16_f32 v124, v132, v133
	s_waitcnt lgkmcnt(4)
	v_mfma_f32_32x32x16_bf16 v[52:67], v[176:179], v[164:167], v[52:67]
	s_cmp_eq_u32 s1, 0
	s_cbranch_scc1 .Lat2_nd1
	s_add_i32 m0, s15, s14
	v_lshl_add_u64 v[214:215], v[184:185], 0, s[94:95]
	global_load_lds_dwordx4 v[214:215], off
